# kernel start: wave 1 samples the grid-sync word during the S5 item's Kt stage and skips the wait behind the item when the sync is already complete
# baseline (speedup 1.0000x reference)
.LBB0_20:
	s_or_b64 exec, exec, s[10:11]
	v_and_b32_e32 v1, 0xffff0000, v1
	s_nop 0
	v_readfirstlane_b32 s99, v1
	s_mov_b64 s[100:101], s[8:9]

.Lssa_471:
	global_load_dword v48, v[4:5], off
	global_load_dword v49, v[6:7], off
	v_add_co_u32_e32 v37, vcc, 0x200, v37
	s_xor_b64 s[84:85], vcc, -1
	s_and_b64 s[84:85], exec, s[84:85]
	v_lshl_add_u64 v[6:7], v[6:7], 0, s[80:81]
	v_lshl_add_u64 v[4:5], v[4:5], 0, s[80:81]
	s_or_b64 s[4:5], s[84:85], s[4:5]
	s_waitcnt vmcnt(0)
	ds_write_b64 v8, v[48:49]
	v_add_u32_e32 v8, 0x1000, v8
	s_andn2_b64 exec, exec, s[4:5]
	s_cbranch_execnz .Lssa_471
	s_or_b64 exec, exec, s[4:5]
	v_mov_b32_e32 v4, 0
	s_mov_b32 s4, 0
	v_mov_b32_e32 v8, v77
	v_mov_b32_e32 v5, v4
	v_mov_b32_e32 v50, v4
	v_mov_b32_e32 v51, v4
	v_mov_b32_e32 v48, v4
	v_mov_b32_e32 v49, v4
	v_mov_b32_e32 v6, v4
	v_mov_b32_e32 v7, v4
	v_mov_b32_e32 v112, v4
	v_mov_b32_e32 v113, v4
	v_mov_b32_e32 v114, v4
	v_mov_b32_e32 v115, v4
	v_mov_b32_e32 v116, v4
	v_mov_b32_e32 v117, v4
	v_mov_b32_e32 v118, v4
	v_mov_b32_e32 v119, v4
	v_and_b32_e32 v12, 14, v208
	v_lshlrev_b32_e32 v12, 3, v12
	v_readfirstlane_b32 s98, v208
	s_cmp_eq_u32 s98, 64
	s_mov_b32 s98, 0
	s_cbranch_scc0 .Lkt_nocg
	v_mov_b32_e32 v15, 0
	global_load_dword v14, v15, s[100:101] offset:32 sc1
.Lkt_nocg:
	s_waitcnt lgkmcnt(0)
	s_barrier
.Lssa_473:
	v_add_u32_e32 v44, s4, v67
	v_add_u32_e32 v37, s4, v76
	v_xor_b32_e32 v37, v12, v37
	ds_read_b128 v[102:105], v44
	ds_read_b128 v[106:109], v37
	ds_read_b128 v[52:55], v8
	ds_read_b128 v[56:59], v8 offset:16
	ds_read_b128 v[60:63], v8 offset:32
	ds_read_b128 v[82:85], v8 offset:48
	ds_read_b128 v[86:89], v8 offset:128
	ds_read_b128 v[90:93], v8 offset:144
	ds_read_b128 v[94:97], v8 offset:160
	ds_read_b128 v[98:101], v8 offset:176
	s_waitcnt lgkmcnt(8)
	v_pk_mul_f32 v[110:111], v[106:107], v[102:103] op_sel:[1,1] op_sel_hi:[0,1]
	v_pk_fma_f32 v[110:111], v[106:107], v[102:103], v[110:111] op_sel_hi:[1,0,1] neg_lo:[0,0,1]
	s_waitcnt lgkmcnt(7)
	v_pk_fma_f32 v[112:113], v[110:111], v[52:53], v[112:113]
	v_pk_fma_f32 v[114:115], v[110:111], v[54:55], v[114:115]
	s_waitcnt lgkmcnt(6)
	v_pk_fma_f32 v[116:117], v[110:111], v[56:57], v[116:117]
	v_pk_fma_f32 v[118:119], v[110:111], v[58:59], v[118:119]
	s_waitcnt lgkmcnt(5)
	v_pk_fma_f32 v[48:49], v[110:111], v[60:61], v[48:49]
	v_pk_fma_f32 v[50:51], v[110:111], v[62:63], v[50:51]
	s_waitcnt lgkmcnt(4)
	v_pk_fma_f32 v[4:5], v[110:111], v[82:83], v[4:5]
	v_pk_fma_f32 v[6:7], v[110:111], v[84:85], v[6:7]
	v_pk_mul_f32 v[110:111], v[108:109], v[104:105] op_sel:[1,1] op_sel_hi:[0,1]
	v_pk_fma_f32 v[110:111], v[108:109], v[104:105], v[110:111] op_sel_hi:[1,0,1] neg_lo:[0,0,1]
	s_waitcnt lgkmcnt(3)
	v_pk_fma_f32 v[112:113], v[110:111], v[86:87], v[112:113]
	v_pk_fma_f32 v[114:115], v[110:111], v[88:89], v[114:115]
	s_waitcnt lgkmcnt(2)
	v_pk_fma_f32 v[116:117], v[110:111], v[90:91], v[116:117]
	v_pk_fma_f32 v[118:119], v[110:111], v[92:93], v[118:119]
	s_waitcnt lgkmcnt(1)
	v_pk_fma_f32 v[48:49], v[110:111], v[94:95], v[48:49]
	v_pk_fma_f32 v[50:51], v[110:111], v[96:97], v[50:51]
	s_waitcnt lgkmcnt(0)
	v_pk_fma_f32 v[4:5], v[110:111], v[98:99], v[4:5]
	v_pk_fma_f32 v[6:7], v[110:111], v[100:101], v[6:7]
	s_add_i32 s4, s4, 16
	v_add_u32_e32 v8, 0x100, v8
	s_cmpk_eq_i32 s4, 0x200
	s_cbranch_scc0 .Lssa_473
	v_readfirstlane_b32 s4, v208
	s_cmp_eq_u32 s4, 64
	s_cbranch_scc0 .Lkt_cgdone
	s_waitcnt vmcnt(0)
	v_and_b32_e32 v14, 0xffff0000, v14
	s_nop 0
	v_readfirstlane_b32 s4, v14
	s_cmp_lg_u32 s4, s99
	s_cselect_b32 s98, 1, 0
.Lkt_cgdone:
	v_sub_f32_e32 v52, v112, v113
	v_sub_f32_e32 v53, v114, v115
	v_sub_f32_e32 v54, v116, v117
	v_sub_f32_e32 v55, v118, v119
	v_sub_f32_e32 v56, v48, v49
	v_sub_f32_e32 v57, v50, v51
	v_sub_f32_e32 v58, v4, v5
	v_sub_f32_e32 v59, v6, v7
	v_mov_b32_e32 v50, v52
	v_mov_b32_e32 v51, v53
	v_mov_b32_e32 v48, v54
	v_mov_b32_e32 v49, v55
	v_mov_b32_e32 v6, v56
	v_mov_b32_e32 v7, v57
	v_mov_b32_e32 v4, v58
	v_mov_b32_e32 v5, v59
	v_lshl_add_u32 v52, s82, 4, v66
	v_ashrrev_i32_e32 v53, 31, v52
	v_mov_b32_e32 v8, 0
	v_mov_b32_e32 v37, 0
	s_and_saveexec_b64 s[4:5], s[42:43]
	s_cbranch_execz .Lssa_476
	s_load_dwordx2 s[84:85], s[22:23], 0x80
	s_waitcnt lgkmcnt(0)
	v_lshl_add_u64 v[54:55], v[52:53], 2, s[84:85]
	global_load_dword v37, v[54:55], off

.Lssa_exit:
	s_mov_b32 s100, 0
	v_readfirstlane_b32 s79, v208
	v_cmp_gt_u32_e64 s[4:5], 32, v208
	v_cmp_eq_u32_e32 vcc, 64, v208
	s_and_saveexec_b64 s[6:7], vcc
	s_cbranch_execz .LBB0_24
	s_cmp_eq_u32 s98, 1
	s_cbranch_scc1 .LBB0_23
	s_load_dwordx2 s[8:9], s[0:1], 0x110
	v_mov_b32_e32 v0, 0
	v_mov_b32_e32 v1, s99
	s_waitcnt lgkmcnt(0)
	global_load_dword v2, v0, s[8:9] offset:32 sc1
	s_waitcnt vmcnt(0)
	v_and_b32_e32 v2, 0xffff0000, v2
	v_cmp_eq_u32_e32 vcc, v2, v1
	s_and_b64 exec, exec, vcc
	s_cbranch_execz .LBB0_23
	s_mov_b64 s[10:11], 0
